# NSA selected-branch loop head: running selection word in a VGPR instead of re-selecting it every tile
# speedup vs baseline: 1.0097x; 1.0000x over previous
; __device__ __forceinline__ void nsa_unit(LAS unsigned char* lds, const unsigned char* hb, const bf16_t* kc, const bf16_t* vct, const float* nsg, bf16_t* omix, int b, int g, int c, int tid) {
;     ...
;     { const bf16_t* Ks = (const bf16_t*)(hb + HB_KS * MiB) + (size_t)bg * SEQ * 64; const bf16_t* Vs = (const bf16_t*)(hb + HB_VST * MiB) + (size_t)bg * 64 * SEQ;
;         zero_ot(ot); lsum = 0.f;
;         TILE_LOOP(Ks, Vs, SEQ, 0, c + 1, {
;             const int m = key0 >> 6; const unsigned sw = m < 32 ? sel0 : (m < 64 ? sel1 : (m < 96 ? sel2 : sel3));
;             const bool lane_valid = ((sw >> (m & 31)) & 1u) != 0u;
;             if (__ballot(lane_valid) != 0ull) { const int dist00 = t - (key0 + 8 * h);
;                 if ((c - m) < 3) tile_soft<1>(ks, vs, qf, ot, lsum, lane_valid, dist00, 0, bt, r, h);
;                 else tile_soft<0>(ks, vs, qf, ot, lsum, lane_valid, dist00, 0, bt, r, h); } });
.LBB0_1018:
	v_lshl_add_u64 v[142:143], s[6:7], 0, v[134:135]
	v_lshl_add_u64 v[138:139], s[76:77], 0, v[0:1]
	v_readlane_b32 s6, v255, 33
	v_sub_u32_e32 v80, v117, v152
	v_lshlrev_b64 v[140:141], 13, v[136:137]
	v_or_b32_e32 v138, v138, v116
	v_readlane_b32 s7, v255, 34
	v_subrev_u32_e32 v0, s4, v80
	v_mov_b32_e32 v137, 0
	s_lshl_b32 s10, s16, 19
	s_sub_i32 s11, 0x7c, s15
	v_lshl_add_u64 v[144:145], s[6:7], 0, v[138:139]
	v_add_u32_e32 v135, 0x1fa0, v0
	s_sub_i32 s12, 0x80, s15
	s_mov_b32 s13, 0
	s_mov_b32 s15, 0
	v_mov_b32_e32 v16, 0
	v_mov_b32_e32 v17, v137
	v_mov_b32_e32 v18, v137
	v_mov_b32_e32 v19, v137
	v_mov_b32_e32 v20, v137
	v_mov_b32_e32 v21, v137
	v_mov_b32_e32 v22, v137
	v_mov_b32_e32 v23, v137
	v_mov_b32_e32 v24, v137
	v_mov_b32_e32 v25, v137
	v_mov_b32_e32 v26, v137
	v_mov_b32_e32 v27, v137
	v_mov_b32_e32 v28, v137
	v_mov_b32_e32 v29, v137
	v_mov_b32_e32 v30, v137
	v_mov_b32_e32 v31, v137
	v_mov_b32_e32 v0, 0
	v_mov_b32_e32 v1, v137
	v_mov_b32_e32 v2, v137
	v_mov_b32_e32 v3, v137
	v_mov_b32_e32 v4, v137
	v_mov_b32_e32 v5, v137
	v_mov_b32_e32 v6, v137
	v_mov_b32_e32 v7, v137
	v_mov_b32_e32 v8, v137
	v_mov_b32_e32 v9, v137
	v_mov_b32_e32 v10, v137
	v_mov_b32_e32 v11, v137
	v_mov_b32_e32 v12, v137
	v_mov_b32_e32 v13, v137
	v_mov_b32_e32 v14, v137
	v_mov_b32_e32 v15, v137
	s_waitcnt lgkmcnt(0)
	s_barrier
	v_mov_b32_e32 v237, v98
	s_add_i32 s6, s15, 2
	s_cmp_gt_u32 s6, s14
	s_cbranch_scc1 .LBB0_1020

; __device__ __forceinline__ void tile_soft_far(LAS const unsigned char* ks, LAS const unsigned char* vs, const bf16x8 (&qf)[4], f32x16 (&ot)[2], float& lsum, bool lane_valid, LAS const float* bt, int r, int h) {
;     const float init = lane_valid ? bt[BT_FAR] : -3.0e38f;
;     const int pr = (r & 0x13) | ((r & 4) << 1) | ((r & 8) >> 1);
;     LAS const unsigned char* kp = ks + pr * 144 + h * 16; LAS const unsigned char* vp = vs + r * 144 + h * 16;
;     bf16x8 k0[4], k1[4], v0[2][2], v1[2][2];
; #pragma unroll
;     for (int kk = 0; kk < 4; ++kk) { k0[kk] = *(LAS const bf16x8*)(kp + kk * 32); k1[kk] = *(LAS const bf16x8*)(kp + 32 * 144 + kk * 32); }
;     __builtin_amdgcn_sched_barrier(0);
;     f32x16 s0, s1;
; #pragma unroll
;     for (int i = 0; i < 16; ++i) { s0[i] = init; s1[i] = init; }
; #pragma unroll
;     for (int kk = 0; kk < 4; ++kk) s0 = MFMA32(k0[kk], qf[kk], s0);
; #pragma unroll
;     for (int mt = 0; mt < 2; ++mt)
; #pragma unroll
;         for (int j = 0; j < 2; ++j) { v0[mt][j] = *(LAS const bf16x8*)(vp + 32 * mt * 144 + 32 * j); v1[mt][j] = *(LAS const bf16x8*)(vp + 32 * mt * 144 + 64 + 32 * j); }
;     __builtin_amdgcn_sched_barrier(0);
;     s1 = MFMA32(k1[0], qf[0], s1); SOFT4(s0, 0);  __builtin_amdgcn_sched_barrier(0);
;     s1 = MFMA32(k1[1], qf[1], s1); SOFT4(s0, 4);  __builtin_amdgcn_sched_barrier(0);
;     s1 = MFMA32(k1[2], qf[2], s1); SOFT4(s0, 8);  __builtin_amdgcn_sched_barrier(0);
;     s1 = MFMA32(k1[3], qf[3], s1); SOFT4(s0, 12); __builtin_amdgcn_sched_barrier(0);
;     const bf16x8 pa = pack_p(s0, 0);
;     ot[0] = MFMA32(v0[0][0], pa, ot[0]); SOFT4(s1, 0);  __builtin_amdgcn_sched_barrier(0);
; __device__ __forceinline__ void nsa_unit(LAS unsigned char* lds, const unsigned char* hb, const bf16_t* kc, const bf16_t* vct, const float* nsg, bf16_t* omix, int b, int g, int c, int tid) {
;     ...
;         TILE_LOOP(Ks, Vs, SEQ, 0, c + 1, {
;             const int m = key0 >> 6; const unsigned sw = m < 32 ? sel0 : (m < 64 ? sel1 : (m < 96 ? sel2 : sel3));
;             const bool lane_valid = ((sw >> (m & 31)) & 1u) != 0u;
;             if (__ballot(lane_valid) != 0ull) { const int dist00 = t - (key0 + 8 * h);
;                 if ((c - m) < 3) tile_soft<1>(ks, vs, qf, ot, lsum, lane_valid, dist00, 0, bt, r, h);
;                 else tile_soft<0>(ks, vs, qf, ot, lsum, lane_valid, dist00, 0, bt, r, h); } });
.LBB0_1020:
	s_and_b32 s16, s15, 1
	v_and_b32_e32 v33, 1, v237
	v_lshrrev_b32_e32 v237, 1, v237
	s_and_b32 s8, s15, 31
	v_cmp_eq_u32_e64 s[6:7], 1, v33
	s_cmp_lg_u32 s8, 31
	s_cbranch_scc1 .Lp3_hw
	s_lshr_b32 s8, s15, 5
	s_cmp_eq_u32 s8, 0
	s_cselect_b64 vcc, -1, 0
	s_cmp_eq_u32 s8, 1
	s_cselect_b64 s[8:9], -1, 0
	v_cndmask_b32_e64 v237, v101, v100, s[8:9]
	v_cndmask_b32_e32 v237, v237, v99, vcc
.Lp3_hw:
	s_cmp_eq_u64 s[6:7], 0
	s_cbranch_scc1 .LBB0_1028
	s_mul_i32 s8, s16, 0x4800
	s_add_i32 s17, s8, 0x100
	s_cmp_le_i32 s15, s11
	s_mov_b64 s[8:9], -1
	s_cbranch_scc0 .LBB0_1025
	v_mov_b32_e32 v64, 0xff61b1e6
	v_cndmask_b32_e64 v64, v64, v234, s[6:7]
	v_add3_u32 v32, s17, v212, v154
	ds_read_b128 v[48:51], v32
	ds_read_b128 v[52:55], v32 offset:32
	ds_read_b128 v[56:59], v32 offset:4608
	ds_read_b128 v[60:63], v32 offset:4640
	ds_read_b128 v[118:121], v32 offset:64
	ds_read_b128 v[160:163], v32 offset:96
	ds_read_b128 v[170:173], v32 offset:4672
	ds_read_b128 v[174:177], v32 offset:4704
	s_waitcnt lgkmcnt(8)
	v_mov_b32_e32 v65, v64
	v_mov_b32_e32 v66, v64
	v_mov_b32_e32 v67, v64
	v_mov_b32_e32 v68, v64
	v_mov_b32_e32 v69, v64
	v_mov_b32_e32 v70, v64
	v_mov_b32_e32 v71, v64
	v_mov_b32_e32 v72, v64
	v_mov_b32_e32 v73, v64
	v_mov_b32_e32 v74, v64
	v_mov_b32_e32 v75, v64
	v_mov_b32_e32 v76, v64
	v_mov_b32_e32 v77, v64
	v_mov_b32_e32 v78, v64
	v_mov_b32_e32 v79, v64
	s_waitcnt lgkmcnt(7)
	s_nop 0
	v_mfma_f32_32x32x16_bf16 v[32:47], v[48:51], v[82:85], v[64:79]
	v_add3_u32 v48, s17, v213, v154
	s_waitcnt lgkmcnt(6)
	v_mfma_f32_32x32x16_bf16 v[32:47], v[52:55], v[86:89], v[32:47]
	s_waitcnt lgkmcnt(3)
	v_mfma_f32_32x32x16_bf16 v[32:47], v[118:121], v[90:93], v[32:47]
	ds_read_b128 v[218:221], v48 offset:9216
	ds_read_b128 v[222:225], v48 offset:9248
	ds_read_b128 v[126:129], v48 offset:9280
	ds_read_b128 v[122:125], v48 offset:9312
	ds_read_b128 v[226:229], v48 offset:13824
	ds_read_b128 v[230:233], v48 offset:13856
	ds_read_b128 v[130:133], v48 offset:13888
	ds_read_b128 v[118:121], v48 offset:13920
	s_waitcnt lgkmcnt(10)
	v_mfma_f32_32x32x16_bf16 v[32:47], v[160:163], v[94:97], v[32:47]
	s_nop 11
	v_exp_f32_e32 v32, v32
	v_exp_f32_e32 v33, v33
	v_exp_f32_e32 v34, v34
	v_exp_f32_e32 v35, v35
	v_add_f32_e32 v48, v137, v32
	v_add_f32_e32 v48, v33, v48
	v_add_f32_e32 v48, v34, v48
	v_add_f32_e32 v48, v35, v48
	v_exp_f32_e32 v36, v36
	v_exp_f32_e32 v37, v37
	v_exp_f32_e32 v38, v38
	v_exp_f32_e32 v39, v39
	v_add_f32_e32 v48, v36, v48
	v_add_f32_e32 v48, v37, v48
	v_add_f32_e32 v48, v38, v48
	v_add_f32_e32 v48, v39, v48
	v_mfma_f32_32x32x16_bf16 v[64:79], v[56:59], v[82:85], v[64:79]
	v_exp_f32_e32 v178, v40
	v_exp_f32_e32 v179, v41
	v_exp_f32_e32 v180, v42
	v_exp_f32_e32 v181, v43
	v_add_f32_e32 v40, v178, v48
	v_add_f32_e32 v40, v179, v40
	v_add_f32_e32 v40, v180, v40
	v_add_f32_e32 v40, v181, v40
	v_mfma_f32_32x32x16_bf16 v[64:79], v[60:63], v[86:89], v[64:79]
	v_exp_f32_e32 v182, v44
	s_waitcnt lgkmcnt(9)
	v_mfma_f32_32x32x16_bf16 v[64:79], v[170:173], v[90:93], v[64:79]
	v_exp_f32_e32 v170, v45
	v_exp_f32_e32 v171, v46
	v_exp_f32_e32 v172, v47
	v_add_f32_e32 v40, v182, v40
	v_add_f32_e32 v40, v170, v40
	v_add_f32_e32 v40, v171, v40
	v_add_f32_e32 v40, v172, v40
	s_waitcnt lgkmcnt(8)
	v_mfma_f32_32x32x16_bf16 v[64:79], v[174:177], v[94:97], v[64:79]
	v_cvt_pk_bf16_f32 v160, v32, v33
	v_cvt_pk_bf16_f32 v161, v34, v35
	v_cvt_pk_bf16_f32 v162, v36, v37
	v_cvt_pk_bf16_f32 v163, v38, v39
	s_nop 7
	v_exp_f32_e32 v173, v64
	v_exp_f32_e32 v174, v65
	s_waitcnt lgkmcnt(7)
	v_mfma_f32_32x32x16_bf16 v[16:31], v[218:221], v[160:163], v[16:31]
	v_exp_f32_e32 v175, v66
	v_exp_f32_e32 v176, v67
	v_add_f32_e32 v32, v173, v40
	v_add_f32_e32 v32, v174, v32
	v_add_f32_e32 v32, v175, v32
	v_add_f32_e32 v64, v176, v32
	v_exp_f32_e32 v68, v68
	v_exp_f32_e32 v69, v69
	s_waitcnt lgkmcnt(3)
	v_mfma_f32_32x32x16_bf16 v[0:15], v[226:229], v[160:163], v[0:15]
	v_exp_f32_e32 v70, v70
	v_exp_f32_e32 v71, v71
	v_add_f32_e32 v64, v68, v64
	v_add_f32_e32 v64, v69, v64
	v_add_f32_e32 v64, v70, v64
	v_add_f32_e32 v160, v71, v64
	v_cvt_pk_bf16_f32 v64, v178, v179
	v_cvt_pk_bf16_f32 v65, v180, v181
	v_cvt_pk_bf16_f32 v66, v182, v170
	v_cvt_pk_bf16_f32 v67, v171, v172
	s_nop 1
	v_mfma_f32_32x32x16_bf16 v[16:31], v[222:225], v[64:67], v[16:31]
	v_exp_f32_e32 v72, v72
	v_exp_f32_e32 v73, v73
	v_exp_f32_e32 v74, v74
	v_exp_f32_e32 v75, v75
	v_add_f32_e32 v160, v72, v160
	v_add_f32_e32 v160, v73, v160
	v_add_f32_e32 v160, v74, v160
	v_add_f32_e32 v160, v75, v160
	s_waitcnt lgkmcnt(2)
	v_mfma_f32_32x32x16_bf16 v[0:15], v[230:233], v[64:67], v[0:15]
	v_exp_f32_e32 v76, v76
	v_exp_f32_e32 v77, v77
	v_exp_f32_e32 v78, v78
	v_exp_f32_e32 v79, v79
	v_add_f32_e32 v64, v76, v160
	v_add_f32_e32 v64, v77, v64
	v_add_f32_e32 v64, v78, v64
	v_add_f32_e32 v160, v79, v64
	v_cvt_pk_bf16_f32 v64, v173, v174
	v_cvt_pk_bf16_f32 v65, v175, v176
	v_cvt_pk_bf16_f32 v66, v68, v69
	v_cvt_pk_bf16_f32 v67, v70, v71
	s_mov_b64 s[8:9], 0
	s_nop 0
	v_mfma_f32_32x32x16_bf16 v[16:31], v[126:129], v[64:67], v[16:31]
	s_waitcnt lgkmcnt(1)
	v_mfma_f32_32x32x16_bf16 v[0:15], v[130:133], v[64:67], v[0:15]
	v_cvt_pk_bf16_f32 v64, v72, v73
	v_cvt_pk_bf16_f32 v65, v74, v75
	v_cvt_pk_bf16_f32 v66, v76, v77
	v_cvt_pk_bf16_f32 v67, v78, v79
	s_nop 1
	v_mfma_f32_32x32x16_bf16 v[16:31], v[122:125], v[64:67], v[16:31]
	s_waitcnt lgkmcnt(0)
	v_mfma_f32_32x32x16_bf16 v[0:15], v[118:121], v[64:67], v[0:15]
